# GEMM K-loops: MFMA segments hold only MFMAs between their barriers (s_setprio 1 moved before the opening barrier, s_setprio 0 behind the closing one, middle 0/1 pair and repeated lgkmcnt(0) dropped);
# speedup vs baseline: 1.0105x; 1.0105x over previous
.LBB0_354:
	s_add_u32 s30, s52, 0xfff80080
	s_addc_u32 s31, s53, -1
	s_add_i32 s76, 0, 0x10000
	s_cmp_eq_u32 s75, 28
	s_cselect_b32 s57, s47, s31
	s_cselect_b32 s56, s67, s30
	s_cselect_b32 s55, s45, s74
	s_cselect_b32 s54, s70, s71
	s_add_i32 s30, 0, 0x14000
	v_add_u32_e32 v156, s76, v141
	v_add_u32_e32 v164, s30, v141
	ds_read_b128 v[144:147], v156
	ds_read_b128 v[148:151], v156 offset:1024
	ds_read_b128 v[152:155], v156 offset:2048
	ds_read_b128 v[156:159], v156 offset:3072
	ds_read_b128 v[160:163], v164
	ds_read_b128 v[168:171], v164 offset:1024
	ds_read_b128 v[176:179], v164 offset:2048
	ds_read_b128 v[180:183], v164 offset:3072
	v_lshl_add_u64 v[164:165], s[52:53], 0, v[136:137]
	s_add_i32 m0, s36, 0xc000
	ds_read_b128 v[198:201], v143
	ds_read_b128 v[202:205], v143 offset:1024
	ds_read_b128 v[206:209], v143 offset:2048
	ds_read_b128 v[210:213], v143 offset:3072
	ds_read_b128 v[214:217], v143 offset:4096
	ds_read_b128 v[218:221], v143 offset:5120
	ds_read_b128 v[222:225], v143 offset:6144
	ds_read_b128 v[226:229], v143 offset:7168
	global_load_lds_dwordx4 v[164:165], off
	v_lshl_add_u64 v[164:165], s[52:53], 0, v[138:139]
	s_add_i32 m0, s36, 0xe000
	s_nop 0
	global_load_lds_dwordx4 v[164:165], off
	s_setprio 1
	s_waitcnt vmcnt(8)
	s_waitcnt lgkmcnt(0)
	s_barrier
	v_mfma_f32_16x16x32_bf16 v[126:129], v[144:147], v[198:201], v[126:129]
	v_mfma_f32_16x16x32_bf16 v[122:125], v[152:155], v[198:201], v[122:125]
	v_mfma_f32_16x16x32_bf16 v[118:121], v[144:147], v[206:209], v[118:121]
	v_mfma_f32_16x16x32_bf16 v[114:117], v[152:155], v[206:209], v[114:117]
	v_mfma_f32_16x16x32_bf16 v[102:105], v[144:147], v[214:217], v[102:105]
	v_mfma_f32_16x16x32_bf16 v[98:101], v[152:155], v[214:217], v[98:101]
	v_mfma_f32_16x16x32_bf16 v[86:89], v[144:147], v[222:225], v[86:89]
	v_mfma_f32_16x16x32_bf16 v[82:85], v[152:155], v[222:225], v[82:85]
	v_mfma_f32_16x16x32_bf16 v[126:129], v[148:151], v[202:205], v[126:129]
	v_mfma_f32_16x16x32_bf16 v[122:125], v[156:159], v[202:205], v[122:125]
	v_mfma_f32_16x16x32_bf16 v[118:121], v[148:151], v[210:213], v[118:121]
	v_mfma_f32_16x16x32_bf16 v[114:117], v[156:159], v[210:213], v[114:117]
	v_mfma_f32_16x16x32_bf16 v[102:105], v[148:151], v[218:221], v[102:105]
	v_mfma_f32_16x16x32_bf16 v[98:101], v[156:159], v[218:221], v[98:101]
	v_mfma_f32_16x16x32_bf16 v[86:89], v[148:151], v[226:229], v[86:89]
	v_mfma_f32_16x16x32_bf16 v[82:85], v[156:159], v[226:229], v[82:85]
	v_mfma_f32_16x16x32_bf16 v[110:113], v[160:163], v[198:201], v[110:113]
	v_mfma_f32_16x16x32_bf16 v[106:109], v[176:179], v[198:201], v[106:109]
	v_mfma_f32_16x16x32_bf16 v[94:97], v[160:163], v[206:209], v[94:97]
	v_mfma_f32_16x16x32_bf16 v[90:93], v[176:179], v[206:209], v[90:93]
	v_mfma_f32_16x16x32_bf16 v[78:81], v[160:163], v[214:217], v[78:81]
	v_mfma_f32_16x16x32_bf16 v[74:77], v[176:179], v[214:217], v[74:77]
	v_mfma_f32_16x16x32_bf16 v[70:73], v[160:163], v[222:225], v[70:73]
	v_mfma_f32_16x16x32_bf16 v[66:69], v[176:179], v[222:225], v[66:69]
	v_mfma_f32_16x16x32_bf16 v[110:113], v[168:171], v[202:205], v[110:113]
	v_mfma_f32_16x16x32_bf16 v[106:109], v[180:183], v[202:205], v[106:109]
	v_mfma_f32_16x16x32_bf16 v[94:97], v[168:171], v[210:213], v[94:97]
	v_mfma_f32_16x16x32_bf16 v[90:93], v[180:183], v[210:213], v[90:93]
	v_mfma_f32_16x16x32_bf16 v[78:81], v[168:171], v[218:221], v[78:81]
	v_mfma_f32_16x16x32_bf16 v[74:77], v[180:183], v[218:221], v[74:77]
	v_mfma_f32_16x16x32_bf16 v[70:73], v[168:171], v[226:229], v[70:73]
	v_mfma_f32_16x16x32_bf16 v[66:69], v[180:183], v[226:229], v[66:69]
	s_barrier
	s_setprio 0
	s_add_i32 s31, s76, s35
	v_lshl_add_u64 v[164:165], s[54:55], 0, v[0:1]
	s_mov_b32 m0, s31
	ds_read_b128 v[198:201], v143 offset:16384
	ds_read_b128 v[202:205], v143 offset:17408
	ds_read_b128 v[206:209], v143 offset:18432
	ds_read_b128 v[210:213], v143 offset:19456
	ds_read_b128 v[214:217], v143 offset:20480
	ds_read_b128 v[218:221], v143 offset:21504
	ds_read_b128 v[222:225], v143 offset:22528
	ds_read_b128 v[226:229], v143 offset:23552
	global_load_lds_dwordx4 v[164:165], off
	s_add_i32 m0, s31, 0x2000
	s_add_u32 s76, s54, 0x80000
	v_lshl_add_u64 v[172:173], s[54:55], 0, v[130:131]
	s_addc_u32 s77, s55, 0
	s_add_i32 s30, s30, s35
	global_load_lds_dwordx4 v[172:173], off
	v_lshl_add_u64 v[184:185], s[76:77], 0, v[0:1]
	s_mov_b32 m0, s30
	v_lshl_add_u64 v[230:231], s[56:57], 0, v[132:133]
	global_load_lds_dwordx4 v[184:185], off
	v_lshl_add_u64 v[184:185], s[76:77], 0, v[130:131]
	s_add_i32 m0, s30, 0x2000
	s_nop 0
	global_load_lds_dwordx4 v[184:185], off
	v_lshl_add_u64 v[184:185], s[56:57], 0, v[134:135]
	s_mov_b32 m0, s36
	s_nop 0
	global_load_lds_dwordx4 v[184:185], off
	s_mov_b32 m0, s37
	s_nop 0
	global_load_lds_dwordx4 v[230:231], off
	s_setprio 1
	s_waitcnt vmcnt(8)
	s_waitcnt lgkmcnt(0)
	s_barrier
	v_mfma_f32_16x16x32_bf16 v[62:65], v[144:147], v[198:201], v[62:65]
	v_mfma_f32_16x16x32_bf16 v[58:61], v[152:155], v[198:201], v[58:61]
	v_mfma_f32_16x16x32_bf16 v[54:57], v[144:147], v[206:209], v[54:57]
	v_mfma_f32_16x16x32_bf16 v[50:53], v[152:155], v[206:209], v[50:53]
	v_mfma_f32_16x16x32_bf16 v[38:41], v[144:147], v[214:217], v[38:41]
	v_mfma_f32_16x16x32_bf16 v[34:37], v[152:155], v[214:217], v[34:37]
	v_mfma_f32_16x16x32_bf16 v[22:25], v[144:147], v[222:225], v[22:25]
	v_mfma_f32_16x16x32_bf16 v[18:21], v[152:155], v[222:225], v[18:21]
	v_mfma_f32_16x16x32_bf16 v[62:65], v[148:151], v[202:205], v[62:65]
	v_mfma_f32_16x16x32_bf16 v[58:61], v[156:159], v[202:205], v[58:61]
	v_mfma_f32_16x16x32_bf16 v[54:57], v[148:151], v[210:213], v[54:57]
	v_mfma_f32_16x16x32_bf16 v[50:53], v[156:159], v[210:213], v[50:53]
	v_mfma_f32_16x16x32_bf16 v[38:41], v[148:151], v[218:221], v[38:41]
	v_mfma_f32_16x16x32_bf16 v[34:37], v[156:159], v[218:221], v[34:37]
	v_mfma_f32_16x16x32_bf16 v[22:25], v[148:151], v[226:229], v[22:25]
	v_mfma_f32_16x16x32_bf16 v[18:21], v[156:159], v[226:229], v[18:21]
	v_mfma_f32_16x16x32_bf16 v[46:49], v[160:163], v[198:201], v[46:49]
	v_mfma_f32_16x16x32_bf16 v[42:45], v[176:179], v[198:201], v[42:45]
	v_mfma_f32_16x16x32_bf16 v[30:33], v[160:163], v[206:209], v[30:33]
	v_mfma_f32_16x16x32_bf16 v[26:29], v[176:179], v[206:209], v[26:29]
	v_mfma_f32_16x16x32_bf16 v[14:17], v[160:163], v[214:217], v[14:17]
	v_mfma_f32_16x16x32_bf16 v[10:13], v[176:179], v[214:217], v[10:13]
	v_mfma_f32_16x16x32_bf16 v[6:9], v[160:163], v[222:225], v[6:9]
	v_mfma_f32_16x16x32_bf16 v[2:5], v[176:179], v[222:225], v[2:5]
	v_mfma_f32_16x16x32_bf16 v[46:49], v[168:171], v[202:205], v[46:49]
	v_mfma_f32_16x16x32_bf16 v[42:45], v[180:183], v[202:205], v[42:45]
	v_mfma_f32_16x16x32_bf16 v[30:33], v[168:171], v[210:213], v[30:33]
	v_mfma_f32_16x16x32_bf16 v[26:29], v[180:183], v[210:213], v[26:29]
	v_mfma_f32_16x16x32_bf16 v[14:17], v[168:171], v[218:221], v[14:17]
	v_mfma_f32_16x16x32_bf16 v[10:13], v[180:183], v[218:221], v[10:13]
	v_mfma_f32_16x16x32_bf16 v[6:9], v[168:171], v[226:229], v[6:9]
	v_mfma_f32_16x16x32_bf16 v[2:5], v[180:183], v[226:229], v[2:5]
	s_barrier
	s_setprio 0
	s_add_i32 s30, 0, 0x18000
	s_add_i32 s31, 0, 0x1c000
	v_add_u32_e32 v156, s30, v141
	v_add_u32_e32 v174, s31, v141
	ds_read_b128 v[144:147], v156
	ds_read_b128 v[148:151], v156 offset:1024
	ds_read_b128 v[152:155], v156 offset:2048
	ds_read_b128 v[156:159], v156 offset:3072
	ds_read_b128 v[160:163], v174
	ds_read_b128 v[168:171], v174 offset:1024
	ds_read_b128 v[176:179], v174 offset:2048
	ds_read_b128 v[180:183], v174 offset:3072
	s_add_u32 s56, s56, 0x80000
	s_addc_u32 s57, s57, 0
	s_mov_b32 m0, s60
	v_lshl_add_u64 v[232:233], s[56:57], 0, v[134:135]
	ds_read_b128 v[198:201], v143 offset:32768
	ds_read_b128 v[202:205], v143 offset:33792
	ds_read_b128 v[206:209], v143 offset:34816
	ds_read_b128 v[210:213], v143 offset:35840
	ds_read_b128 v[214:217], v143 offset:36864
	ds_read_b128 v[218:221], v143 offset:37888
	ds_read_b128 v[222:225], v143 offset:38912
	ds_read_b128 v[226:229], v143 offset:39936
	global_load_lds_dwordx4 v[232:233], off
	v_lshl_add_u64 v[232:233], s[56:57], 0, v[132:133]
	s_mov_b32 m0, s61
	s_nop 0
	global_load_lds_dwordx4 v[232:233], off
	s_setprio 1
	s_waitcnt vmcnt(8)
	s_waitcnt lgkmcnt(0)
	s_barrier
	v_mfma_f32_16x16x32_bf16 v[126:129], v[144:147], v[198:201], v[126:129]
	v_mfma_f32_16x16x32_bf16 v[122:125], v[152:155], v[198:201], v[122:125]
	v_mfma_f32_16x16x32_bf16 v[118:121], v[144:147], v[206:209], v[118:121]
	v_mfma_f32_16x16x32_bf16 v[114:117], v[152:155], v[206:209], v[114:117]
	v_mfma_f32_16x16x32_bf16 v[102:105], v[144:147], v[214:217], v[102:105]
	v_mfma_f32_16x16x32_bf16 v[98:101], v[152:155], v[214:217], v[98:101]
	v_mfma_f32_16x16x32_bf16 v[86:89], v[144:147], v[222:225], v[86:89]
	v_mfma_f32_16x16x32_bf16 v[82:85], v[152:155], v[222:225], v[82:85]
	v_mfma_f32_16x16x32_bf16 v[126:129], v[148:151], v[202:205], v[126:129]
	v_mfma_f32_16x16x32_bf16 v[122:125], v[156:159], v[202:205], v[122:125]
	v_mfma_f32_16x16x32_bf16 v[118:121], v[148:151], v[210:213], v[118:121]
	v_mfma_f32_16x16x32_bf16 v[114:117], v[156:159], v[210:213], v[114:117]
	v_mfma_f32_16x16x32_bf16 v[102:105], v[148:151], v[218:221], v[102:105]
	v_mfma_f32_16x16x32_bf16 v[98:101], v[156:159], v[218:221], v[98:101]
	v_mfma_f32_16x16x32_bf16 v[86:89], v[148:151], v[226:229], v[86:89]
	v_mfma_f32_16x16x32_bf16 v[82:85], v[156:159], v[226:229], v[82:85]
	v_mfma_f32_16x16x32_bf16 v[110:113], v[160:163], v[198:201], v[110:113]
	v_mfma_f32_16x16x32_bf16 v[106:109], v[176:179], v[198:201], v[106:109]
	v_mfma_f32_16x16x32_bf16 v[94:97], v[160:163], v[206:209], v[94:97]
	v_mfma_f32_16x16x32_bf16 v[90:93], v[176:179], v[206:209], v[90:93]
	v_mfma_f32_16x16x32_bf16 v[78:81], v[160:163], v[214:217], v[78:81]
	v_mfma_f32_16x16x32_bf16 v[74:77], v[176:179], v[214:217], v[74:77]
	v_mfma_f32_16x16x32_bf16 v[70:73], v[160:163], v[222:225], v[70:73]
	v_mfma_f32_16x16x32_bf16 v[66:69], v[176:179], v[222:225], v[66:69]
	v_mfma_f32_16x16x32_bf16 v[110:113], v[168:171], v[202:205], v[110:113]
	v_mfma_f32_16x16x32_bf16 v[106:109], v[180:183], v[202:205], v[106:109]
	v_mfma_f32_16x16x32_bf16 v[94:97], v[168:171], v[210:213], v[94:97]
	v_mfma_f32_16x16x32_bf16 v[90:93], v[180:183], v[210:213], v[90:93]
	v_mfma_f32_16x16x32_bf16 v[78:81], v[168:171], v[218:221], v[78:81]
	v_mfma_f32_16x16x32_bf16 v[74:77], v[180:183], v[218:221], v[74:77]
	v_mfma_f32_16x16x32_bf16 v[70:73], v[168:171], v[226:229], v[70:73]
	v_mfma_f32_16x16x32_bf16 v[66:69], v[180:183], v[226:229], v[66:69]
	s_barrier
	s_setprio 0
	s_add_i32 s30, s30, s35
	v_lshl_add_u64 v[164:165], v[164:165], 0, s[38:39]
	s_mov_b32 m0, s30
	ds_read_b128 v[198:201], v143 offset:49152
	ds_read_b128 v[202:205], v143 offset:50176
	ds_read_b128 v[206:209], v143 offset:51200
	ds_read_b128 v[210:213], v143 offset:52224
	ds_read_b128 v[214:217], v143 offset:53248
	ds_read_b128 v[218:221], v143 offset:54272
	ds_read_b128 v[222:225], v143 offset:55296
	ds_read_b128 v[226:229], v143 offset:56320
	global_load_lds_dwordx4 v[164:165], off
	s_add_i32 m0, s30, 0x2000
	s_add_u32 s54, s54, 0x80080
	v_lshl_add_u64 v[164:165], v[172:173], 0, s[38:39]
	s_addc_u32 s55, s55, 0
	s_add_i32 s30, s31, s35
	global_load_lds_dwordx4 v[164:165], off
	v_lshl_add_u64 v[164:165], s[54:55], 0, v[0:1]
	s_mov_b32 m0, s30
	s_nop 0
	global_load_lds_dwordx4 v[164:165], off
	v_lshl_add_u64 v[164:165], s[54:55], 0, v[130:131]
	s_add_i32 m0, s30, 0x2000
	s_nop 0
	global_load_lds_dwordx4 v[164:165], off
	v_lshl_add_u64 v[164:165], v[184:185], 0, s[38:39]
	s_mov_b32 m0, s62
	s_nop 0
	global_load_lds_dwordx4 v[164:165], off
	v_lshl_add_u64 v[164:165], v[230:231], 0, s[38:39]
	s_mov_b32 m0, s63
	s_nop 0
	global_load_lds_dwordx4 v[164:165], off
	s_setprio 1
	s_waitcnt vmcnt(8)
	s_waitcnt lgkmcnt(0)
	s_barrier
	v_mfma_f32_16x16x32_bf16 v[62:65], v[144:147], v[198:201], v[62:65]
	v_mfma_f32_16x16x32_bf16 v[58:61], v[152:155], v[198:201], v[58:61]
	v_mfma_f32_16x16x32_bf16 v[54:57], v[144:147], v[206:209], v[54:57]
	v_mfma_f32_16x16x32_bf16 v[50:53], v[152:155], v[206:209], v[50:53]
	v_mfma_f32_16x16x32_bf16 v[38:41], v[144:147], v[214:217], v[38:41]
	v_mfma_f32_16x16x32_bf16 v[34:37], v[152:155], v[214:217], v[34:37]
	v_mfma_f32_16x16x32_bf16 v[22:25], v[144:147], v[222:225], v[22:25]
	v_mfma_f32_16x16x32_bf16 v[18:21], v[152:155], v[222:225], v[18:21]
	v_mfma_f32_16x16x32_bf16 v[62:65], v[148:151], v[202:205], v[62:65]
	v_mfma_f32_16x16x32_bf16 v[58:61], v[156:159], v[202:205], v[58:61]
	v_mfma_f32_16x16x32_bf16 v[54:57], v[148:151], v[210:213], v[54:57]
	v_mfma_f32_16x16x32_bf16 v[50:53], v[156:159], v[210:213], v[50:53]
	v_mfma_f32_16x16x32_bf16 v[38:41], v[148:151], v[218:221], v[38:41]
	v_mfma_f32_16x16x32_bf16 v[34:37], v[156:159], v[218:221], v[34:37]
	v_mfma_f32_16x16x32_bf16 v[22:25], v[148:151], v[226:229], v[22:25]
	v_mfma_f32_16x16x32_bf16 v[18:21], v[156:159], v[226:229], v[18:21]
	v_mfma_f32_16x16x32_bf16 v[46:49], v[160:163], v[198:201], v[46:49]
	v_mfma_f32_16x16x32_bf16 v[42:45], v[176:179], v[198:201], v[42:45]
	v_mfma_f32_16x16x32_bf16 v[30:33], v[160:163], v[206:209], v[30:33]
	v_mfma_f32_16x16x32_bf16 v[26:29], v[176:179], v[206:209], v[26:29]
	v_mfma_f32_16x16x32_bf16 v[14:17], v[160:163], v[214:217], v[14:17]
	v_mfma_f32_16x16x32_bf16 v[10:13], v[176:179], v[214:217], v[10:13]
	v_mfma_f32_16x16x32_bf16 v[6:9], v[160:163], v[222:225], v[6:9]
	v_mfma_f32_16x16x32_bf16 v[2:5], v[176:179], v[222:225], v[2:5]
	v_mfma_f32_16x16x32_bf16 v[46:49], v[168:171], v[202:205], v[46:49]
	v_mfma_f32_16x16x32_bf16 v[42:45], v[180:183], v[202:205], v[42:45]
	v_mfma_f32_16x16x32_bf16 v[30:33], v[168:171], v[210:213], v[30:33]
	v_mfma_f32_16x16x32_bf16 v[26:29], v[180:183], v[210:213], v[26:29]
	v_mfma_f32_16x16x32_bf16 v[14:17], v[168:171], v[218:221], v[14:17]
	v_mfma_f32_16x16x32_bf16 v[10:13], v[180:183], v[218:221], v[10:13]
	v_mfma_f32_16x16x32_bf16 v[6:9], v[168:171], v[226:229], v[6:9]
	v_mfma_f32_16x16x32_bf16 v[2:5], v[180:183], v[226:229], v[2:5]
	s_barrier
	s_setprio 0
	s_add_i32 s75, s75, 2
	s_add_u32 s52, s52, 0x100
	s_addc_u32 s53, s53, 0
	s_add_u32 s71, s71, 0x100
	s_addc_u32 s74, s74, 0
	s_cmp_gt_u32 s75, 29
	s_cbranch_scc0 .LBB0_354
	s_and_b64 vcc, exec, s[42:43]
	s_cbranch_vccz .LBB0_357
	s_barrier

.LBB0_1089:
	s_add_u32 s30, s20, 0xfff80080
	s_addc_u32 s31, s21, -1
	s_add_i32 s77, 0, 0x10000
	s_cmp_eq_u32 s76, 28
	s_cselect_b32 vcc_hi, s43, s31
	s_cselect_b32 vcc_lo, s49, s30
	s_cselect_b32 s53, s67, s75
	s_cselect_b32 s52, s71, s74
	s_add_i32 s30, 0, 0x14000
	v_add_u32_e32 v156, s77, v145
	v_add_u32_e32 v164, s30, v145
	ds_read_b128 v[140:143], v156
	ds_read_b128 v[148:151], v156 offset:1024
	ds_read_b128 v[152:155], v156 offset:2048
	ds_read_b128 v[156:159], v156 offset:3072
	ds_read_b128 v[160:163], v164
	ds_read_b128 v[168:171], v164 offset:1024
	ds_read_b128 v[176:179], v164 offset:2048
	ds_read_b128 v[180:183], v164 offset:3072
	v_lshl_add_u64 v[164:165], s[20:21], 0, v[136:137]
	s_add_i32 m0, s55, 0xc000
	ds_read_b128 v[198:201], v147
	ds_read_b128 v[202:205], v147 offset:1024
	ds_read_b128 v[206:209], v147 offset:2048
	ds_read_b128 v[210:213], v147 offset:3072
	ds_read_b128 v[214:217], v147 offset:4096
	ds_read_b128 v[218:221], v147 offset:5120
	ds_read_b128 v[222:225], v147 offset:6144
	ds_read_b128 v[226:229], v147 offset:7168
	global_load_lds_dwordx4 v[164:165], off
	v_lshl_add_u64 v[164:165], s[20:21], 0, v[138:139]
	s_add_i32 m0, s55, 0xe000
	s_nop 0
	global_load_lds_dwordx4 v[164:165], off
	s_setprio 1
	s_waitcnt vmcnt(8)
	s_waitcnt lgkmcnt(0)
	s_barrier
	v_mfma_f32_16x16x32_bf16 v[126:129], v[140:143], v[198:201], v[126:129]
	v_mfma_f32_16x16x32_bf16 v[118:121], v[152:155], v[198:201], v[118:121]
	v_mfma_f32_16x16x32_bf16 v[110:113], v[140:143], v[206:209], v[110:113]
	v_mfma_f32_16x16x32_bf16 v[102:105], v[152:155], v[206:209], v[102:105]
	v_mfma_f32_16x16x32_bf16 v[94:97], v[140:143], v[214:217], v[94:97]
	v_mfma_f32_16x16x32_bf16 v[86:89], v[152:155], v[214:217], v[86:89]
	v_mfma_f32_16x16x32_bf16 v[78:81], v[140:143], v[222:225], v[78:81]
	v_mfma_f32_16x16x32_bf16 v[70:73], v[152:155], v[222:225], v[70:73]
	v_mfma_f32_16x16x32_bf16 v[126:129], v[148:151], v[202:205], v[126:129]
	v_mfma_f32_16x16x32_bf16 v[118:121], v[156:159], v[202:205], v[118:121]
	v_mfma_f32_16x16x32_bf16 v[110:113], v[148:151], v[210:213], v[110:113]
	v_mfma_f32_16x16x32_bf16 v[102:105], v[156:159], v[210:213], v[102:105]
	v_mfma_f32_16x16x32_bf16 v[94:97], v[148:151], v[218:221], v[94:97]
	v_mfma_f32_16x16x32_bf16 v[86:89], v[156:159], v[218:221], v[86:89]
	v_mfma_f32_16x16x32_bf16 v[78:81], v[148:151], v[226:229], v[78:81]
	v_mfma_f32_16x16x32_bf16 v[70:73], v[156:159], v[226:229], v[70:73]
	v_mfma_f32_16x16x32_bf16 v[122:125], v[160:163], v[198:201], v[122:125]
	v_mfma_f32_16x16x32_bf16 v[114:117], v[176:179], v[198:201], v[114:117]
	v_mfma_f32_16x16x32_bf16 v[106:109], v[160:163], v[206:209], v[106:109]
	v_mfma_f32_16x16x32_bf16 v[98:101], v[176:179], v[206:209], v[98:101]
	v_mfma_f32_16x16x32_bf16 v[90:93], v[160:163], v[214:217], v[90:93]
	v_mfma_f32_16x16x32_bf16 v[82:85], v[176:179], v[214:217], v[82:85]
	v_mfma_f32_16x16x32_bf16 v[74:77], v[160:163], v[222:225], v[74:77]
	v_mfma_f32_16x16x32_bf16 v[66:69], v[176:179], v[222:225], v[66:69]
	v_mfma_f32_16x16x32_bf16 v[122:125], v[168:171], v[202:205], v[122:125]
	v_mfma_f32_16x16x32_bf16 v[114:117], v[180:183], v[202:205], v[114:117]
	v_mfma_f32_16x16x32_bf16 v[106:109], v[168:171], v[210:213], v[106:109]
	v_mfma_f32_16x16x32_bf16 v[98:101], v[180:183], v[210:213], v[98:101]
	v_mfma_f32_16x16x32_bf16 v[90:93], v[168:171], v[218:221], v[90:93]
	v_mfma_f32_16x16x32_bf16 v[82:85], v[180:183], v[218:221], v[82:85]
	v_mfma_f32_16x16x32_bf16 v[74:77], v[168:171], v[226:229], v[74:77]
	v_mfma_f32_16x16x32_bf16 v[66:69], v[180:183], v[226:229], v[66:69]
	s_barrier
	s_setprio 0
	s_add_i32 s31, s77, s6
	v_lshl_add_u64 v[164:165], s[52:53], 0, v[0:1]
	s_mov_b32 m0, s31
	ds_read_b128 v[198:201], v147 offset:16384
	ds_read_b128 v[202:205], v147 offset:17408
	ds_read_b128 v[206:209], v147 offset:18432
	ds_read_b128 v[210:213], v147 offset:19456
	ds_read_b128 v[214:217], v147 offset:20480
	ds_read_b128 v[218:221], v147 offset:21504
	ds_read_b128 v[222:225], v147 offset:22528
	ds_read_b128 v[226:229], v147 offset:23552
	global_load_lds_dwordx4 v[164:165], off
	s_add_i32 m0, s31, 0x2000
	s_add_u32 s78, s52, 0x80000
	v_lshl_add_u64 v[172:173], s[52:53], 0, v[130:131]
	s_addc_u32 s79, s53, 0
	s_add_i32 s30, s30, s6
	global_load_lds_dwordx4 v[172:173], off
	v_lshl_add_u64 v[184:185], s[78:79], 0, v[0:1]
	s_mov_b32 m0, s30
	v_lshl_add_u64 v[230:231], vcc, 0, v[132:133]
	global_load_lds_dwordx4 v[184:185], off
	v_lshl_add_u64 v[184:185], s[78:79], 0, v[130:131]
	s_add_i32 m0, s30, 0x2000
	s_nop 0
	global_load_lds_dwordx4 v[184:185], off
	v_lshl_add_u64 v[184:185], vcc, 0, v[134:135]
	s_mov_b32 m0, s55
	s_nop 0
	global_load_lds_dwordx4 v[184:185], off
	s_mov_b32 m0, s97
	s_nop 0
	global_load_lds_dwordx4 v[230:231], off
	s_setprio 1
	s_waitcnt vmcnt(8)
	s_waitcnt lgkmcnt(0)
	s_barrier
	v_mfma_f32_16x16x32_bf16 v[62:65], v[140:143], v[198:201], v[62:65]
	v_mfma_f32_16x16x32_bf16 v[54:57], v[152:155], v[198:201], v[54:57]
	v_mfma_f32_16x16x32_bf16 v[46:49], v[140:143], v[206:209], v[46:49]
	v_mfma_f32_16x16x32_bf16 v[38:41], v[152:155], v[206:209], v[38:41]
	v_mfma_f32_16x16x32_bf16 v[30:33], v[140:143], v[214:217], v[30:33]
	v_mfma_f32_16x16x32_bf16 v[22:25], v[152:155], v[214:217], v[22:25]
	v_mfma_f32_16x16x32_bf16 v[14:17], v[140:143], v[222:225], v[14:17]
	v_mfma_f32_16x16x32_bf16 v[6:9], v[152:155], v[222:225], v[6:9]
	v_mfma_f32_16x16x32_bf16 v[62:65], v[148:151], v[202:205], v[62:65]
	v_mfma_f32_16x16x32_bf16 v[54:57], v[156:159], v[202:205], v[54:57]
	v_mfma_f32_16x16x32_bf16 v[46:49], v[148:151], v[210:213], v[46:49]
	v_mfma_f32_16x16x32_bf16 v[38:41], v[156:159], v[210:213], v[38:41]
	v_mfma_f32_16x16x32_bf16 v[30:33], v[148:151], v[218:221], v[30:33]
	v_mfma_f32_16x16x32_bf16 v[22:25], v[156:159], v[218:221], v[22:25]
	v_mfma_f32_16x16x32_bf16 v[14:17], v[148:151], v[226:229], v[14:17]
	v_mfma_f32_16x16x32_bf16 v[6:9], v[156:159], v[226:229], v[6:9]
	v_mfma_f32_16x16x32_bf16 v[58:61], v[160:163], v[198:201], v[58:61]
	v_mfma_f32_16x16x32_bf16 v[50:53], v[176:179], v[198:201], v[50:53]
	v_mfma_f32_16x16x32_bf16 v[42:45], v[160:163], v[206:209], v[42:45]
	v_mfma_f32_16x16x32_bf16 v[34:37], v[176:179], v[206:209], v[34:37]
	v_mfma_f32_16x16x32_bf16 v[26:29], v[160:163], v[214:217], v[26:29]
	v_mfma_f32_16x16x32_bf16 v[18:21], v[176:179], v[214:217], v[18:21]
	v_mfma_f32_16x16x32_bf16 v[10:13], v[160:163], v[222:225], v[10:13]
	v_mfma_f32_16x16x32_bf16 v[2:5], v[176:179], v[222:225], v[2:5]
	v_mfma_f32_16x16x32_bf16 v[58:61], v[168:171], v[202:205], v[58:61]
	v_mfma_f32_16x16x32_bf16 v[50:53], v[180:183], v[202:205], v[50:53]
	v_mfma_f32_16x16x32_bf16 v[42:45], v[168:171], v[210:213], v[42:45]
	v_mfma_f32_16x16x32_bf16 v[34:37], v[180:183], v[210:213], v[34:37]
	v_mfma_f32_16x16x32_bf16 v[26:29], v[168:171], v[218:221], v[26:29]
	v_mfma_f32_16x16x32_bf16 v[18:21], v[180:183], v[218:221], v[18:21]
	v_mfma_f32_16x16x32_bf16 v[10:13], v[168:171], v[226:229], v[10:13]
	v_mfma_f32_16x16x32_bf16 v[2:5], v[180:183], v[226:229], v[2:5]
	s_barrier
	s_setprio 0
	s_add_i32 s30, 0, 0x18000
	s_add_i32 s31, 0, 0x1c000
	v_add_u32_e32 v156, s30, v145
	v_add_u32_e32 v174, s31, v145
	ds_read_b128 v[140:143], v156
	ds_read_b128 v[148:151], v156 offset:1024
	ds_read_b128 v[152:155], v156 offset:2048
	ds_read_b128 v[156:159], v156 offset:3072
	ds_read_b128 v[160:163], v174
	ds_read_b128 v[168:171], v174 offset:1024
	ds_read_b128 v[176:179], v174 offset:2048
	ds_read_b128 v[180:183], v174 offset:3072
	s_add_u32 s78, vcc_lo, 0x80000
	s_addc_u32 s79, vcc_hi, 0
	s_mov_b32 m0, s34
	v_lshl_add_u64 v[232:233], s[78:79], 0, v[134:135]
	ds_read_b128 v[198:201], v147 offset:32768
	ds_read_b128 v[202:205], v147 offset:33792
	ds_read_b128 v[206:209], v147 offset:34816
	ds_read_b128 v[210:213], v147 offset:35840
	ds_read_b128 v[214:217], v147 offset:36864
	ds_read_b128 v[218:221], v147 offset:37888
	ds_read_b128 v[222:225], v147 offset:38912
	ds_read_b128 v[226:229], v147 offset:39936
	global_load_lds_dwordx4 v[232:233], off
	v_lshl_add_u64 v[232:233], s[78:79], 0, v[132:133]
	s_mov_b32 m0, s35
	s_nop 0
	global_load_lds_dwordx4 v[232:233], off
	s_setprio 1
	s_waitcnt vmcnt(8)
	s_waitcnt lgkmcnt(0)
	s_barrier
	v_mfma_f32_16x16x32_bf16 v[126:129], v[140:143], v[198:201], v[126:129]
	v_mfma_f32_16x16x32_bf16 v[118:121], v[152:155], v[198:201], v[118:121]
	v_mfma_f32_16x16x32_bf16 v[110:113], v[140:143], v[206:209], v[110:113]
	v_mfma_f32_16x16x32_bf16 v[102:105], v[152:155], v[206:209], v[102:105]
	v_mfma_f32_16x16x32_bf16 v[94:97], v[140:143], v[214:217], v[94:97]
	v_mfma_f32_16x16x32_bf16 v[86:89], v[152:155], v[214:217], v[86:89]
	v_mfma_f32_16x16x32_bf16 v[78:81], v[140:143], v[222:225], v[78:81]
	v_mfma_f32_16x16x32_bf16 v[70:73], v[152:155], v[222:225], v[70:73]
	v_mfma_f32_16x16x32_bf16 v[126:129], v[148:151], v[202:205], v[126:129]
	v_mfma_f32_16x16x32_bf16 v[118:121], v[156:159], v[202:205], v[118:121]
	v_mfma_f32_16x16x32_bf16 v[110:113], v[148:151], v[210:213], v[110:113]
	v_mfma_f32_16x16x32_bf16 v[102:105], v[156:159], v[210:213], v[102:105]
	v_mfma_f32_16x16x32_bf16 v[94:97], v[148:151], v[218:221], v[94:97]
	v_mfma_f32_16x16x32_bf16 v[86:89], v[156:159], v[218:221], v[86:89]
	v_mfma_f32_16x16x32_bf16 v[78:81], v[148:151], v[226:229], v[78:81]
	v_mfma_f32_16x16x32_bf16 v[70:73], v[156:159], v[226:229], v[70:73]
	v_mfma_f32_16x16x32_bf16 v[122:125], v[160:163], v[198:201], v[122:125]
	v_mfma_f32_16x16x32_bf16 v[114:117], v[176:179], v[198:201], v[114:117]
	v_mfma_f32_16x16x32_bf16 v[106:109], v[160:163], v[206:209], v[106:109]
	v_mfma_f32_16x16x32_bf16 v[98:101], v[176:179], v[206:209], v[98:101]
	v_mfma_f32_16x16x32_bf16 v[90:93], v[160:163], v[214:217], v[90:93]
	v_mfma_f32_16x16x32_bf16 v[82:85], v[176:179], v[214:217], v[82:85]
	v_mfma_f32_16x16x32_bf16 v[74:77], v[160:163], v[222:225], v[74:77]
	v_mfma_f32_16x16x32_bf16 v[66:69], v[176:179], v[222:225], v[66:69]
	v_mfma_f32_16x16x32_bf16 v[122:125], v[168:171], v[202:205], v[122:125]
	v_mfma_f32_16x16x32_bf16 v[114:117], v[180:183], v[202:205], v[114:117]
	v_mfma_f32_16x16x32_bf16 v[106:109], v[168:171], v[210:213], v[106:109]
	v_mfma_f32_16x16x32_bf16 v[98:101], v[180:183], v[210:213], v[98:101]
	v_mfma_f32_16x16x32_bf16 v[90:93], v[168:171], v[218:221], v[90:93]
	v_mfma_f32_16x16x32_bf16 v[82:85], v[180:183], v[218:221], v[82:85]
	v_mfma_f32_16x16x32_bf16 v[74:77], v[168:171], v[226:229], v[74:77]
	v_mfma_f32_16x16x32_bf16 v[66:69], v[180:183], v[226:229], v[66:69]
	s_barrier
	s_setprio 0
	s_add_i32 s30, s30, s6
	v_lshl_add_u64 v[164:165], v[164:165], 0, s[38:39]
	s_mov_b32 m0, s30
	ds_read_b128 v[198:201], v147 offset:49152
	ds_read_b128 v[202:205], v147 offset:50176
	ds_read_b128 v[206:209], v147 offset:51200
	ds_read_b128 v[210:213], v147 offset:52224
	ds_read_b128 v[214:217], v147 offset:53248
	ds_read_b128 v[218:221], v147 offset:54272
	ds_read_b128 v[222:225], v147 offset:55296
	ds_read_b128 v[226:229], v147 offset:56320
	global_load_lds_dwordx4 v[164:165], off
	s_add_i32 m0, s30, 0x2000
	s_add_u32 s52, s52, 0x80080
	v_lshl_add_u64 v[164:165], v[172:173], 0, s[38:39]
	s_addc_u32 s53, s53, 0
	s_add_i32 s30, s31, s6
	global_load_lds_dwordx4 v[164:165], off
	v_lshl_add_u64 v[164:165], s[52:53], 0, v[0:1]
	s_mov_b32 m0, s30
	s_nop 0
	global_load_lds_dwordx4 v[164:165], off
	v_lshl_add_u64 v[164:165], s[52:53], 0, v[130:131]
	s_add_i32 m0, s30, 0x2000
	s_nop 0
	global_load_lds_dwordx4 v[164:165], off
	v_lshl_add_u64 v[164:165], v[184:185], 0, s[38:39]
	s_mov_b32 m0, s36
	s_nop 0
	global_load_lds_dwordx4 v[164:165], off
	v_lshl_add_u64 v[164:165], v[230:231], 0, s[38:39]
	s_mov_b32 m0, s37
	s_nop 0
	global_load_lds_dwordx4 v[164:165], off
	s_setprio 1
	s_waitcnt vmcnt(8)
	s_waitcnt lgkmcnt(0)
	s_barrier
	v_mfma_f32_16x16x32_bf16 v[62:65], v[140:143], v[198:201], v[62:65]
	v_mfma_f32_16x16x32_bf16 v[54:57], v[152:155], v[198:201], v[54:57]
	v_mfma_f32_16x16x32_bf16 v[46:49], v[140:143], v[206:209], v[46:49]
	v_mfma_f32_16x16x32_bf16 v[38:41], v[152:155], v[206:209], v[38:41]
	v_mfma_f32_16x16x32_bf16 v[30:33], v[140:143], v[214:217], v[30:33]
	v_mfma_f32_16x16x32_bf16 v[22:25], v[152:155], v[214:217], v[22:25]
	v_mfma_f32_16x16x32_bf16 v[14:17], v[140:143], v[222:225], v[14:17]
	v_mfma_f32_16x16x32_bf16 v[6:9], v[152:155], v[222:225], v[6:9]
	v_mfma_f32_16x16x32_bf16 v[62:65], v[148:151], v[202:205], v[62:65]
	v_mfma_f32_16x16x32_bf16 v[54:57], v[156:159], v[202:205], v[54:57]
	v_mfma_f32_16x16x32_bf16 v[46:49], v[148:151], v[210:213], v[46:49]
	v_mfma_f32_16x16x32_bf16 v[38:41], v[156:159], v[210:213], v[38:41]
	v_mfma_f32_16x16x32_bf16 v[30:33], v[148:151], v[218:221], v[30:33]
	v_mfma_f32_16x16x32_bf16 v[22:25], v[156:159], v[218:221], v[22:25]
	v_mfma_f32_16x16x32_bf16 v[14:17], v[148:151], v[226:229], v[14:17]
	v_mfma_f32_16x16x32_bf16 v[6:9], v[156:159], v[226:229], v[6:9]
	v_mfma_f32_16x16x32_bf16 v[58:61], v[160:163], v[198:201], v[58:61]
	v_mfma_f32_16x16x32_bf16 v[50:53], v[176:179], v[198:201], v[50:53]
	v_mfma_f32_16x16x32_bf16 v[42:45], v[160:163], v[206:209], v[42:45]
	v_mfma_f32_16x16x32_bf16 v[34:37], v[176:179], v[206:209], v[34:37]
	v_mfma_f32_16x16x32_bf16 v[26:29], v[160:163], v[214:217], v[26:29]
	v_mfma_f32_16x16x32_bf16 v[18:21], v[176:179], v[214:217], v[18:21]
	v_mfma_f32_16x16x32_bf16 v[10:13], v[160:163], v[222:225], v[10:13]
	v_mfma_f32_16x16x32_bf16 v[2:5], v[176:179], v[222:225], v[2:5]
	v_mfma_f32_16x16x32_bf16 v[58:61], v[168:171], v[202:205], v[58:61]
	v_mfma_f32_16x16x32_bf16 v[50:53], v[180:183], v[202:205], v[50:53]
	v_mfma_f32_16x16x32_bf16 v[42:45], v[168:171], v[210:213], v[42:45]
	v_mfma_f32_16x16x32_bf16 v[34:37], v[180:183], v[210:213], v[34:37]
	v_mfma_f32_16x16x32_bf16 v[26:29], v[168:171], v[218:221], v[26:29]
	v_mfma_f32_16x16x32_bf16 v[18:21], v[180:183], v[218:221], v[18:21]
	v_mfma_f32_16x16x32_bf16 v[10:13], v[168:171], v[226:229], v[10:13]
	v_mfma_f32_16x16x32_bf16 v[2:5], v[180:183], v[226:229], v[2:5]
	s_barrier
	s_setprio 0
	s_add_i32 s76, s76, 2
	s_add_u32 s20, s20, 0x100
	s_addc_u32 s21, s21, 0
	s_add_u32 s74, s74, 0x100
	s_addc_u32 s75, s75, 0
	s_cmp_gt_u32 s76, 29
	s_cbranch_scc0 .LBB0_1089
	s_and_b64 vcc, exec, s[64:65]
	s_cbranch_vccz .LBB0_1092
	s_barrier

.LBB0_1185:
	s_add_i32 s96, s66, 2
	s_add_u32 s30, s52, 0x80
	s_addc_u32 s31, s53, 0
	s_add_i32 s25, 0, 0x10000
	s_cmp_eq_u32 s77, s66
	s_cselect_b32 s67, s1, s31
	s_cselect_b32 s66, s0, s30
	v_add_u32_e32 v148, s25, v151
	s_cselect_b32 s31, s63, vcc_hi
	s_cselect_b32 s30, s62, vcc_lo
	s_add_i32 s28, 0, 0x14000
	ds_read_b128 v[140:143], v148
	ds_read_b128 v[144:147], v148 offset:1024
	ds_read_b128 v[154:157], v148 offset:2048
	ds_read_b128 v[158:161], v148 offset:3072
	v_add_u32_e32 v148, s28, v151
	ds_read_b128 v[162:165], v148
	ds_read_b128 v[168:171], v148 offset:1024
	ds_read_b128 v[176:179], v148 offset:2048
	ds_read_b128 v[180:183], v148 offset:3072
	v_lshl_add_u64 v[148:149], s[52:53], 0, v[136:137]
	s_add_i32 m0, s54, 0xc000
	ds_read_b128 v[198:201], v153
	ds_read_b128 v[202:205], v153 offset:1024
	ds_read_b128 v[206:209], v153 offset:2048
	ds_read_b128 v[210:213], v153 offset:3072
	ds_read_b128 v[214:217], v153 offset:4096
	ds_read_b128 v[218:221], v153 offset:5120
	ds_read_b128 v[222:225], v153 offset:6144
	ds_read_b128 v[226:229], v153 offset:7168
	global_load_lds_dwordx4 v[148:149], off
	v_lshl_add_u64 v[148:149], s[52:53], 0, v[138:139]
	s_add_i32 m0, s54, 0xe000
	s_nop 0
	global_load_lds_dwordx4 v[148:149], off
	s_setprio 1
	s_waitcnt vmcnt(8)
	s_waitcnt lgkmcnt(0)
	s_barrier
	v_mfma_f32_16x16x32_bf16 v[2:5], v[140:143], v[198:201], v[2:5]
	v_mfma_f32_16x16x32_bf16 v[6:9], v[154:157], v[198:201], v[6:9]
	v_mfma_f32_16x16x32_bf16 v[10:13], v[140:143], v[206:209], v[10:13]
	v_mfma_f32_16x16x32_bf16 v[14:17], v[154:157], v[206:209], v[14:17]
	v_mfma_f32_16x16x32_bf16 v[26:29], v[140:143], v[214:217], v[26:29]
	v_mfma_f32_16x16x32_bf16 v[30:33], v[154:157], v[214:217], v[30:33]
	v_mfma_f32_16x16x32_bf16 v[42:45], v[140:143], v[222:225], v[42:45]
	v_mfma_f32_16x16x32_bf16 v[46:49], v[154:157], v[222:225], v[46:49]
	v_mfma_f32_16x16x32_bf16 v[2:5], v[144:147], v[202:205], v[2:5]
	v_mfma_f32_16x16x32_bf16 v[6:9], v[158:161], v[202:205], v[6:9]
	v_mfma_f32_16x16x32_bf16 v[10:13], v[144:147], v[210:213], v[10:13]
	v_mfma_f32_16x16x32_bf16 v[14:17], v[158:161], v[210:213], v[14:17]
	v_mfma_f32_16x16x32_bf16 v[26:29], v[144:147], v[218:221], v[26:29]
	v_mfma_f32_16x16x32_bf16 v[30:33], v[158:161], v[218:221], v[30:33]
	v_mfma_f32_16x16x32_bf16 v[42:45], v[144:147], v[226:229], v[42:45]
	v_mfma_f32_16x16x32_bf16 v[46:49], v[158:161], v[226:229], v[46:49]
	v_mfma_f32_16x16x32_bf16 v[18:21], v[162:165], v[198:201], v[18:21]
	v_mfma_f32_16x16x32_bf16 v[22:25], v[176:179], v[198:201], v[22:25]
	v_mfma_f32_16x16x32_bf16 v[34:37], v[162:165], v[206:209], v[34:37]
	v_mfma_f32_16x16x32_bf16 v[38:41], v[176:179], v[206:209], v[38:41]
	v_mfma_f32_16x16x32_bf16 v[50:53], v[162:165], v[214:217], v[50:53]
	v_mfma_f32_16x16x32_bf16 v[54:57], v[176:179], v[214:217], v[54:57]
	v_mfma_f32_16x16x32_bf16 v[58:61], v[162:165], v[222:225], v[58:61]
	v_mfma_f32_16x16x32_bf16 v[66:69], v[176:179], v[222:225], v[66:69]
	v_mfma_f32_16x16x32_bf16 v[18:21], v[168:171], v[202:205], v[18:21]
	v_mfma_f32_16x16x32_bf16 v[22:25], v[180:183], v[202:205], v[22:25]
	v_mfma_f32_16x16x32_bf16 v[34:37], v[168:171], v[210:213], v[34:37]
	v_mfma_f32_16x16x32_bf16 v[38:41], v[180:183], v[210:213], v[38:41]
	v_mfma_f32_16x16x32_bf16 v[50:53], v[168:171], v[218:221], v[50:53]
	v_mfma_f32_16x16x32_bf16 v[54:57], v[180:183], v[218:221], v[54:57]
	v_mfma_f32_16x16x32_bf16 v[58:61], v[168:171], v[226:229], v[58:61]
	v_mfma_f32_16x16x32_bf16 v[66:69], v[180:183], v[226:229], v[66:69]
	s_barrier
	s_setprio 0
	s_add_i32 s25, s25, s37
	v_lshl_add_u64 v[148:149], s[30:31], 0, v[0:1]
	s_mov_b32 m0, s25
	ds_read_b128 v[198:201], v153 offset:16384
	ds_read_b128 v[202:205], v153 offset:17408
	ds_read_b128 v[206:209], v153 offset:18432
	ds_read_b128 v[210:213], v153 offset:19456
	ds_read_b128 v[214:217], v153 offset:20480
	ds_read_b128 v[218:221], v153 offset:21504
	ds_read_b128 v[222:225], v153 offset:22528
	ds_read_b128 v[226:229], v153 offset:23552
	global_load_lds_dwordx4 v[148:149], off
	s_add_i32 m0, s25, 0x2000
	v_lshl_add_u64 v[172:173], s[30:31], 0, v[130:131]
	s_add_u32 s30, s30, s34
	s_addc_u32 s31, s31, 0
	s_add_i32 s25, s28, s37
	global_load_lds_dwordx4 v[172:173], off
	v_lshl_add_u64 v[184:185], s[30:31], 0, v[0:1]
	s_mov_b32 m0, s25
	v_lshl_add_u64 v[230:231], s[30:31], 0, v[130:131]
	global_load_lds_dwordx4 v[184:185], off
	s_add_i32 m0, s25, 0x2000
	v_lshl_add_u64 v[232:233], s[66:67], 0, v[134:135]
	global_load_lds_dwordx4 v[230:231], off
	s_mov_b32 m0, s54
	v_lshl_add_u64 v[234:235], s[66:67], 0, v[132:133]
	global_load_lds_dwordx4 v[232:233], off
	s_mov_b32 m0, s55
	s_nop 0
	global_load_lds_dwordx4 v[234:235], off
	s_setprio 1
	s_waitcnt vmcnt(8)
	s_waitcnt lgkmcnt(0)
	s_barrier
	v_mfma_f32_16x16x32_bf16 v[62:65], v[140:143], v[198:201], v[62:65]
	v_mfma_f32_16x16x32_bf16 v[70:73], v[154:157], v[198:201], v[70:73]
	v_mfma_f32_16x16x32_bf16 v[74:77], v[140:143], v[206:209], v[74:77]
	v_mfma_f32_16x16x32_bf16 v[86:89], v[154:157], v[206:209], v[86:89]
	v_mfma_f32_16x16x32_bf16 v[90:93], v[140:143], v[214:217], v[90:93]
	v_mfma_f32_16x16x32_bf16 v[94:97], v[154:157], v[214:217], v[94:97]
	v_mfma_f32_16x16x32_bf16 v[102:105], v[140:143], v[222:225], v[102:105]
	v_mfma_f32_16x16x32_bf16 v[110:113], v[154:157], v[222:225], v[110:113]
	v_mfma_f32_16x16x32_bf16 v[62:65], v[144:147], v[202:205], v[62:65]
	v_mfma_f32_16x16x32_bf16 v[70:73], v[158:161], v[202:205], v[70:73]
	v_mfma_f32_16x16x32_bf16 v[74:77], v[144:147], v[210:213], v[74:77]
	v_mfma_f32_16x16x32_bf16 v[86:89], v[158:161], v[210:213], v[86:89]
	v_mfma_f32_16x16x32_bf16 v[90:93], v[144:147], v[218:221], v[90:93]
	v_mfma_f32_16x16x32_bf16 v[94:97], v[158:161], v[218:221], v[94:97]
	v_mfma_f32_16x16x32_bf16 v[102:105], v[144:147], v[226:229], v[102:105]
	v_mfma_f32_16x16x32_bf16 v[110:113], v[158:161], v[226:229], v[110:113]
	v_mfma_f32_16x16x32_bf16 v[78:81], v[162:165], v[198:201], v[78:81]
	v_mfma_f32_16x16x32_bf16 v[82:85], v[176:179], v[198:201], v[82:85]
	v_mfma_f32_16x16x32_bf16 v[98:101], v[162:165], v[206:209], v[98:101]
	v_mfma_f32_16x16x32_bf16 v[106:109], v[176:179], v[206:209], v[106:109]
	v_mfma_f32_16x16x32_bf16 v[114:117], v[162:165], v[214:217], v[114:117]
	v_mfma_f32_16x16x32_bf16 v[118:121], v[176:179], v[214:217], v[118:121]
	v_mfma_f32_16x16x32_bf16 v[122:125], v[162:165], v[222:225], v[122:125]
	v_mfma_f32_16x16x32_bf16 v[126:129], v[176:179], v[222:225], v[126:129]
	v_mfma_f32_16x16x32_bf16 v[78:81], v[168:171], v[202:205], v[78:81]
	v_mfma_f32_16x16x32_bf16 v[82:85], v[180:183], v[202:205], v[82:85]
	v_mfma_f32_16x16x32_bf16 v[98:101], v[168:171], v[210:213], v[98:101]
	v_mfma_f32_16x16x32_bf16 v[106:109], v[180:183], v[210:213], v[106:109]
	v_mfma_f32_16x16x32_bf16 v[114:117], v[168:171], v[218:221], v[114:117]
	v_mfma_f32_16x16x32_bf16 v[118:121], v[180:183], v[218:221], v[118:121]
	v_mfma_f32_16x16x32_bf16 v[122:125], v[168:171], v[226:229], v[122:125]
	v_mfma_f32_16x16x32_bf16 v[126:129], v[180:183], v[226:229], v[126:129]
	s_barrier
	s_setprio 0
	s_add_i32 s25, 0, 0x18000
	s_add_i32 s28, 0, 0x1c000
	v_add_u32_e32 v158, s25, v151
	v_add_u32_e32 v174, s28, v151
	ds_read_b128 v[140:143], v158
	ds_read_b128 v[144:147], v158 offset:1024
	ds_read_b128 v[154:157], v158 offset:2048
	ds_read_b128 v[158:161], v158 offset:3072
	ds_read_b128 v[162:165], v174
	ds_read_b128 v[168:171], v174 offset:1024
	ds_read_b128 v[176:179], v174 offset:2048
	ds_read_b128 v[180:183], v174 offset:3072
	s_add_u32 s30, s66, s6
	s_addc_u32 s31, s67, 0
	s_mov_b32 m0, s70
	v_lshl_add_u64 v[236:237], s[30:31], 0, v[134:135]
	ds_read_b128 v[198:201], v153 offset:32768
	ds_read_b128 v[202:205], v153 offset:33792
	ds_read_b128 v[206:209], v153 offset:34816
	ds_read_b128 v[210:213], v153 offset:35840
	ds_read_b128 v[214:217], v153 offset:36864
	ds_read_b128 v[218:221], v153 offset:37888
	ds_read_b128 v[222:225], v153 offset:38912
	ds_read_b128 v[226:229], v153 offset:39936
	global_load_lds_dwordx4 v[236:237], off
	v_lshl_add_u64 v[236:237], s[30:31], 0, v[132:133]
	s_mov_b32 m0, s71
	s_nop 0
	global_load_lds_dwordx4 v[236:237], off
	s_setprio 1
	s_waitcnt vmcnt(8)
	s_waitcnt lgkmcnt(0)
	s_barrier
	v_mfma_f32_16x16x32_bf16 v[2:5], v[140:143], v[198:201], v[2:5]
	v_mfma_f32_16x16x32_bf16 v[6:9], v[154:157], v[198:201], v[6:9]
	v_mfma_f32_16x16x32_bf16 v[10:13], v[140:143], v[206:209], v[10:13]
	v_mfma_f32_16x16x32_bf16 v[14:17], v[154:157], v[206:209], v[14:17]
	v_mfma_f32_16x16x32_bf16 v[26:29], v[140:143], v[214:217], v[26:29]
	v_mfma_f32_16x16x32_bf16 v[30:33], v[154:157], v[214:217], v[30:33]
	v_mfma_f32_16x16x32_bf16 v[42:45], v[140:143], v[222:225], v[42:45]
	v_mfma_f32_16x16x32_bf16 v[46:49], v[154:157], v[222:225], v[46:49]
	v_mfma_f32_16x16x32_bf16 v[2:5], v[144:147], v[202:205], v[2:5]
	v_mfma_f32_16x16x32_bf16 v[6:9], v[158:161], v[202:205], v[6:9]
	v_mfma_f32_16x16x32_bf16 v[10:13], v[144:147], v[210:213], v[10:13]
	v_mfma_f32_16x16x32_bf16 v[14:17], v[158:161], v[210:213], v[14:17]
	v_mfma_f32_16x16x32_bf16 v[26:29], v[144:147], v[218:221], v[26:29]
	v_mfma_f32_16x16x32_bf16 v[30:33], v[158:161], v[218:221], v[30:33]
	v_mfma_f32_16x16x32_bf16 v[42:45], v[144:147], v[226:229], v[42:45]
	v_mfma_f32_16x16x32_bf16 v[46:49], v[158:161], v[226:229], v[46:49]
	v_mfma_f32_16x16x32_bf16 v[18:21], v[162:165], v[198:201], v[18:21]
	v_mfma_f32_16x16x32_bf16 v[22:25], v[176:179], v[198:201], v[22:25]
	v_mfma_f32_16x16x32_bf16 v[34:37], v[162:165], v[206:209], v[34:37]
	v_mfma_f32_16x16x32_bf16 v[38:41], v[176:179], v[206:209], v[38:41]
	v_mfma_f32_16x16x32_bf16 v[50:53], v[162:165], v[214:217], v[50:53]
	v_mfma_f32_16x16x32_bf16 v[54:57], v[176:179], v[214:217], v[54:57]
	v_mfma_f32_16x16x32_bf16 v[58:61], v[162:165], v[222:225], v[58:61]
	v_mfma_f32_16x16x32_bf16 v[66:69], v[176:179], v[222:225], v[66:69]
	v_mfma_f32_16x16x32_bf16 v[18:21], v[168:171], v[202:205], v[18:21]
	v_mfma_f32_16x16x32_bf16 v[22:25], v[180:183], v[202:205], v[22:25]
	v_mfma_f32_16x16x32_bf16 v[34:37], v[168:171], v[210:213], v[34:37]
	v_mfma_f32_16x16x32_bf16 v[38:41], v[180:183], v[210:213], v[38:41]
	v_mfma_f32_16x16x32_bf16 v[50:53], v[168:171], v[218:221], v[50:53]
	v_mfma_f32_16x16x32_bf16 v[54:57], v[180:183], v[218:221], v[54:57]
	v_mfma_f32_16x16x32_bf16 v[58:61], v[168:171], v[226:229], v[58:61]
	v_mfma_f32_16x16x32_bf16 v[66:69], v[180:183], v[226:229], v[66:69]
	s_barrier
	s_setprio 0
	s_add_i32 s25, s25, s37
	v_lshl_add_u64 v[148:149], v[148:149], 0, s[38:39]
	s_mov_b32 m0, s25
	ds_read_b128 v[198:201], v153 offset:49152
	ds_read_b128 v[202:205], v153 offset:50176
	ds_read_b128 v[206:209], v153 offset:51200
	ds_read_b128 v[210:213], v153 offset:52224
	ds_read_b128 v[214:217], v153 offset:53248
	ds_read_b128 v[218:221], v153 offset:54272
	ds_read_b128 v[222:225], v153 offset:55296
	ds_read_b128 v[226:229], v153 offset:56320
	global_load_lds_dwordx4 v[148:149], off
	v_lshl_add_u64 v[148:149], v[172:173], 0, s[38:39]
	s_add_i32 m0, s25, 0x2000
	s_add_i32 s25, s28, s37
	global_load_lds_dwordx4 v[148:149], off
	v_lshl_add_u64 v[148:149], v[184:185], 0, s[38:39]
	s_mov_b32 m0, s25
	s_nop 0
	global_load_lds_dwordx4 v[148:149], off
	v_lshl_add_u64 v[148:149], v[230:231], 0, s[38:39]
	s_add_i32 m0, s25, 0x2000
	s_nop 0
	global_load_lds_dwordx4 v[148:149], off
	v_lshl_add_u64 v[148:149], v[232:233], 0, s[38:39]
	s_mov_b32 m0, s74
	s_nop 0
	global_load_lds_dwordx4 v[148:149], off
	v_lshl_add_u64 v[148:149], v[234:235], 0, s[38:39]
	s_mov_b32 m0, s75
	s_nop 0
	global_load_lds_dwordx4 v[148:149], off
	s_setprio 1
	s_waitcnt vmcnt(8)
	s_waitcnt lgkmcnt(0)
	s_barrier
	v_mfma_f32_16x16x32_bf16 v[62:65], v[140:143], v[198:201], v[62:65]
	v_mfma_f32_16x16x32_bf16 v[70:73], v[154:157], v[198:201], v[70:73]
	v_mfma_f32_16x16x32_bf16 v[74:77], v[140:143], v[206:209], v[74:77]
	v_mfma_f32_16x16x32_bf16 v[86:89], v[154:157], v[206:209], v[86:89]
	v_mfma_f32_16x16x32_bf16 v[90:93], v[140:143], v[214:217], v[90:93]
	v_mfma_f32_16x16x32_bf16 v[94:97], v[154:157], v[214:217], v[94:97]
	v_mfma_f32_16x16x32_bf16 v[102:105], v[140:143], v[222:225], v[102:105]
	v_mfma_f32_16x16x32_bf16 v[110:113], v[154:157], v[222:225], v[110:113]
	v_mfma_f32_16x16x32_bf16 v[62:65], v[144:147], v[202:205], v[62:65]
	v_mfma_f32_16x16x32_bf16 v[70:73], v[158:161], v[202:205], v[70:73]
	v_mfma_f32_16x16x32_bf16 v[74:77], v[144:147], v[210:213], v[74:77]
	v_mfma_f32_16x16x32_bf16 v[86:89], v[158:161], v[210:213], v[86:89]
	v_mfma_f32_16x16x32_bf16 v[90:93], v[144:147], v[218:221], v[90:93]
	v_mfma_f32_16x16x32_bf16 v[94:97], v[158:161], v[218:221], v[94:97]
	v_mfma_f32_16x16x32_bf16 v[102:105], v[144:147], v[226:229], v[102:105]
	v_mfma_f32_16x16x32_bf16 v[110:113], v[158:161], v[226:229], v[110:113]
	v_mfma_f32_16x16x32_bf16 v[78:81], v[162:165], v[198:201], v[78:81]
	v_mfma_f32_16x16x32_bf16 v[82:85], v[176:179], v[198:201], v[82:85]
	v_mfma_f32_16x16x32_bf16 v[98:101], v[162:165], v[206:209], v[98:101]
	v_mfma_f32_16x16x32_bf16 v[106:109], v[176:179], v[206:209], v[106:109]
	v_mfma_f32_16x16x32_bf16 v[114:117], v[162:165], v[214:217], v[114:117]
	v_mfma_f32_16x16x32_bf16 v[118:121], v[176:179], v[214:217], v[118:121]
	v_mfma_f32_16x16x32_bf16 v[122:125], v[162:165], v[222:225], v[122:125]
	v_mfma_f32_16x16x32_bf16 v[126:129], v[176:179], v[222:225], v[126:129]
	v_mfma_f32_16x16x32_bf16 v[78:81], v[168:171], v[202:205], v[78:81]
	v_mfma_f32_16x16x32_bf16 v[82:85], v[180:183], v[202:205], v[82:85]
	v_mfma_f32_16x16x32_bf16 v[98:101], v[168:171], v[210:213], v[98:101]
	v_mfma_f32_16x16x32_bf16 v[106:109], v[180:183], v[210:213], v[106:109]
	v_mfma_f32_16x16x32_bf16 v[114:117], v[168:171], v[218:221], v[114:117]
	v_mfma_f32_16x16x32_bf16 v[118:121], v[180:183], v[218:221], v[118:121]
	v_mfma_f32_16x16x32_bf16 v[122:125], v[168:171], v[226:229], v[122:125]
	v_mfma_f32_16x16x32_bf16 v[126:129], v[180:183], v[226:229], v[126:129]
	s_barrier
	s_setprio 0
	s_add_u32 s52, s52, 0x100
	s_addc_u32 s53, s53, 0
	s_add_u32 vcc_lo, vcc_lo, 0x100
	s_addc_u32 vcc_hi, vcc_hi, 0
	s_cmp_ge_u32 s96, s76
	s_mov_b32 s66, s96
	s_cbranch_scc0 .LBB0_1185
	s_and_b64 vcc, exec, s[60:61]
	s_cbranch_vccz .LBB0_1188
	s_barrier
